# outproj value loop: five fragment reads hoisted above the DMA block (DMA temporaries moved to late fragments), counted LDS waits
# baseline (speedup 1.0000x reference)
; DI void phase_outproj(const Params& P, char* shm) {
;     ...
;     O_ISSUE(0, 0, 0);
;     O_ISSUE(0, 1, 1);
;     asm volatile("s_waitcnt vmcnt(6)" ::: "memory");
;     asm volatile("s_waitcnt lgkmcnt(0)" ::: "memory");
;     __builtin_amdgcn_s_barrier();
;     int cur = 0, nxt = 2;
;     ...
;       for (int q = 0; q < 8; ++q) {
;         const bool more = (q < 6) || (x < 3);
;         if (q < 6) O_ISSUE(x, 18 + q, nxt);
;         else if (x < 3) O_ISSUE(x + 1, q - 6, nxt);
.LBB0_847:
	s_mul_i32 s98, s11, 0xc000
	v_or_b32_e32 v250, s98, v220
	v_add_u32_e32 v251, s98, v219
	ds_read_b128 v[222:225], v250 offset:32768
	ds_read_b128 v[226:229], v250 offset:34816
	ds_read_b128 v[230:233], v251
	ds_read_b128 v[234:237], v251 offset:2048
	ds_read_b128 v[238:241], v251 offset:4096
	s_cmp_lt_u32 s48, 6
	s_cselect_b64 s[20:21], -1, 0
	s_and_b64 vcc, exec, s[20:21]
	s_cbranch_vccnz .LBB0_849
	s_mov_b32 s53, 0x10000
	s_mov_b32 s52, 0x20000
	s_mov_b32 s49, 0x30000
	s_mov_b64 s[22:23], s[18:19]
	s_mov_b64 s[24:25], s[8:9]
	v_add_u32_e32 v242, 0xfffffe80, v128
	s_mov_b64 s[26:27], s[16:17]
	s_andn2_b64 vcc, exec, s[26:27]
	s_cbranch_vccz .LBB0_850
	s_branch .LBB0_851
.LBB0_849:
	s_mov_b32 s53, 0x8000
	s_mov_b32 s52, 0x10000
	s_mov_b32 s49, 0x18000
	s_mov_b64 s[22:23], s[14:15]
	s_mov_b64 s[24:25], s[12:13]
	v_add_u32_e32 v242, 0x80, v218
	s_mov_b64 s[26:27], s[20:21]
	s_andn2_b64 vcc, exec, s[26:27]
	s_cbranch_vccnz .LBB0_851
.LBB0_850:
	v_add_u32_e32 v244, s47, v242
	s_mul_i32 s26, s45, 0xc000
	v_add_u32_e32 v254, s26, v217
	v_ashrrev_i32_e32 v245, 31, v244
	v_lshlrev_b64 v[244:245], 1, v[244:245]
	v_readfirstlane_b32 s26, v254
	v_lshl_add_u64 v[246:247], s[24:25], 0, v[244:245]
	s_mov_b32 m0, s26
	s_add_i32 s26, s47, s53
	global_load_lds_dwordx4 v[246:247], off
	v_add_u32_e32 v246, s26, v242
	v_ashrrev_i32_e32 v247, 31, v246
	v_add_u32_e32 v243, 0x2000, v254
	v_lshlrev_b64 v[246:247], 1, v[246:247]
	v_readfirstlane_b32 s26, v243
	v_lshl_add_u64 v[248:249], s[24:25], 0, v[246:247]
	s_mov_b32 m0, s26
	s_add_i32 s26, s47, s52
	v_add_u32_e32 v243, 0x4000, v254
	global_load_lds_dwordx4 v[248:249], off
	v_add_u32_e32 v248, s26, v242
	v_readfirstlane_b32 s26, v243
	v_ashrrev_i32_e32 v249, 31, v248
	s_mov_b32 m0, s26
	s_add_i32 s26, s47, s49
	v_lshl_add_u64 v[248:249], v[248:249], 1, s[24:25]
	v_add_u32_e32 v242, s26, v242
	global_load_lds_dwordx4 v[248:249], off
	v_ashrrev_i32_e32 v243, 31, v242
	v_add_u32_e32 v248, 0x6000, v254
	v_lshl_add_u64 v[242:243], v[242:243], 1, s[24:25]
	v_readfirstlane_b32 s24, v248
	v_add_u32_e32 v248, 0x8000, v254
	s_mov_b32 m0, s24
	v_readfirstlane_b32 s24, v248
	global_load_lds_dwordx4 v[242:243], off
	v_lshl_add_u64 v[242:243], s[22:23], 0, v[244:245]
	s_mov_b32 m0, s24
	v_add_u32_e32 v244, 0xa000, v254
	global_load_lds_dwordx4 v[242:243], off
	v_lshl_add_u64 v[242:243], s[22:23], 0, v[246:247]
	v_readfirstlane_b32 s22, v244
	s_mov_b32 m0, s22
	s_nop 0
	global_load_lds_dwordx4 v[242:243], off
.LBB0_851:
	s_or_b64 s[20:21], s[16:17], s[20:21]
	ds_read_b128 v[242:245], v251 offset:6144
	ds_read_b128 v[246:249], v251 offset:8192
	s_waitcnt lgkmcnt(4)
	v_mfma_f32_16x16x32_bf16 v[116:119], v[222:225], v[230:233], v[116:119]
	v_mfma_f32_16x16x32_bf16 v[108:111], v[226:229], v[230:233], v[108:111]
	ds_read_b128 v[230:233], v251 offset:10240
	s_waitcnt lgkmcnt(4)
	v_mfma_f32_16x16x32_bf16 v[104:107], v[222:225], v[234:237], v[104:107]
	v_mfma_f32_16x16x32_bf16 v[96:99], v[226:229], v[234:237], v[96:99]
	ds_read_b128 v[234:237], v251 offset:12288
	s_waitcnt lgkmcnt(4)
	v_mfma_f32_16x16x32_bf16 v[92:95], v[222:225], v[238:241], v[92:95]
	v_mfma_f32_16x16x32_bf16 v[84:87], v[226:229], v[238:241], v[84:87]
	ds_read_b128 v[238:241], v251 offset:14336
	s_waitcnt lgkmcnt(4)
	v_mfma_f32_16x16x32_bf16 v[80:83], v[222:225], v[242:245], v[80:83]
	v_mfma_f32_16x16x32_bf16 v[72:75], v[226:229], v[242:245], v[72:75]
	s_waitcnt lgkmcnt(3)
	v_mfma_f32_16x16x32_bf16 v[68:71], v[222:225], v[246:249], v[68:71]
	v_mfma_f32_16x16x32_bf16 v[60:63], v[226:229], v[246:249], v[60:63]
	s_waitcnt lgkmcnt(2)
	v_mfma_f32_16x16x32_bf16 v[52:55], v[222:225], v[230:233], v[52:55]
	v_mfma_f32_16x16x32_bf16 v[48:51], v[226:229], v[230:233], v[48:51]
	s_waitcnt lgkmcnt(1)
	v_mfma_f32_16x16x32_bf16 v[40:43], v[222:225], v[234:237], v[40:43]
	v_mfma_f32_16x16x32_bf16 v[36:39], v[226:229], v[234:237], v[36:39]
	s_waitcnt lgkmcnt(0)
	v_mfma_f32_16x16x32_bf16 v[28:31], v[222:225], v[238:241], v[28:31]
	v_mfma_f32_16x16x32_bf16 v[12:15], v[226:229], v[238:241], v[12:15]
	ds_read_b128 v[222:225], v250 offset:33792
	ds_read_b128 v[226:229], v250 offset:35840
	ds_read_b128 v[230:233], v251 offset:1024
	ds_read_b128 v[234:237], v251 offset:3072
	ds_read_b128 v[238:241], v251 offset:5120
	ds_read_b128 v[242:245], v251 offset:7168
	ds_read_b128 v[246:249], v251 offset:9216
	s_waitcnt lgkmcnt(4)
	v_mfma_f32_16x16x32_bf16 v[116:119], v[222:225], v[230:233], v[116:119]
	v_mfma_f32_16x16x32_bf16 v[108:111], v[226:229], v[230:233], v[108:111]
	ds_read_b128 v[230:233], v251 offset:11264
	s_waitcnt lgkmcnt(4)
	v_mfma_f32_16x16x32_bf16 v[104:107], v[222:225], v[234:237], v[104:107]
	v_mfma_f32_16x16x32_bf16 v[96:99], v[226:229], v[234:237], v[96:99]
	ds_read_b128 v[234:237], v251 offset:13312
	s_waitcnt lgkmcnt(4)
	v_mfma_f32_16x16x32_bf16 v[92:95], v[222:225], v[238:241], v[92:95]
	v_mfma_f32_16x16x32_bf16 v[84:87], v[226:229], v[238:241], v[84:87]
	ds_read_b128 v[238:241], v251 offset:15360
	s_waitcnt lgkmcnt(4)
	v_mfma_f32_16x16x32_bf16 v[80:83], v[222:225], v[242:245], v[80:83]
	v_mfma_f32_16x16x32_bf16 v[72:75], v[226:229], v[242:245], v[72:75]
	s_waitcnt lgkmcnt(3)
	v_mfma_f32_16x16x32_bf16 v[68:71], v[222:225], v[246:249], v[68:71]
	v_mfma_f32_16x16x32_bf16 v[60:63], v[226:229], v[246:249], v[60:63]
	s_waitcnt lgkmcnt(2)
	v_mfma_f32_16x16x32_bf16 v[52:55], v[222:225], v[230:233], v[52:55]
	v_mfma_f32_16x16x32_bf16 v[48:51], v[226:229], v[230:233], v[48:51]
	s_waitcnt lgkmcnt(1)
	v_mfma_f32_16x16x32_bf16 v[40:43], v[222:225], v[234:237], v[40:43]
	v_mfma_f32_16x16x32_bf16 v[36:39], v[226:229], v[234:237], v[36:39]
	s_waitcnt lgkmcnt(0)
	v_mfma_f32_16x16x32_bf16 v[28:31], v[222:225], v[238:241], v[28:31]
	v_mfma_f32_16x16x32_bf16 v[12:15], v[226:229], v[238:241], v[12:15]
	s_waitcnt lgkmcnt(0)
	s_andn2_b64 vcc, exec, s[20:21]
	s_mov_b64 s[20:21], -1
	s_cbranch_vccz .LBB0_853
	s_waitcnt vmcnt(0)
	s_mov_b64 s[20:21], 0
